# e32: e29 + the out_w/glu_w weight-transpose items (466..831) move from HBM-bound P1 into the slack of P3's pool workgroups (same loop code, entered with vcu:=128+ridx)
# speedup vs baseline: 1.0078x; 1.0078x over previous
; #define LAS __attribute__((address_space(3)))
; __device__ __forceinline__ f32x4 ld_nt(const float* p) { return __builtin_nontemporal_load((const f32x4*)p); }
; #define SUB(i, ...) do { if (PROBE_PH == phk && PROBE_SUB == (i)) { __syncthreads(); tp0 = __builtin_amdgcn_s_memrealtime(); } __VA_ARGS__ if (PROBE_PH == phk && PROBE_SUB == (i)) { asm volatile("s_waitcnt vmcnt(0)" ::: "memory"); __syncthreads(); tp1 = __builtin_amdgcn_s_memrealtime(); } } while (0)
; __device__ __forceinline__ void transpose_item(const float* W, int K, int pitch, int ncols, f16* WT, LAS float* scr, int item, int lane) {
;     const int nblk = ncols / 32, kb = item / nblk, nb = item % nblk, k0 = 64 * kb, n0 = 32 * nb;
;     const int kr = lane >> 3, nq = (lane & 7) * 4;
;     f32x4 v[8];
; #pragma unroll
;     for (int i = 0; i < 8; ++i) v[i] = ld_nt(W + (size_t)(k0 + kr + 8 * i) * pitch + n0 + nq);
; __global__ void __launch_bounds__(NTHREADS, 2) mk_fwd(Args a) {
;     ...
;         SUB(2, if (vcu < 128) transpose_dispatch((320 + vcu) * 8 + wave, a.in[7], a.in[20], a.in[18], a.in[8], a.ws, scr, lane);
;                else { const int b2 = vcu - 128;
;                    for (int it = 448 + 3 * b2; it < 448 + 3 * b2 + 3; ++it) transpose_dispatch(it * 8 + wave, a.in[7], a.in[20], a.in[18], a.in[8], a.ws, scr, lane);
;                    if (b2 < 16) transpose_dispatch((832 + b2) * 8 + wave, a.in[7], a.in[20], a.in[18], a.in[8], a.ws, scr, lane); } );
.LBB0_184:
	s_mov_b32 s99, 0
	s_mul_i32 s2, s53, 0x2100
	s_mov_b32 s13, 0
	s_add_i32 s28, s2, 0
	s_mov_b64 s[2:3], -1
	s_and_b64 vcc, exec, s[18:19]
	s_cbranch_vccz .LBB0_230
.Lp1_tr_setup:
	v_readlane_b32 s56, v254, 2
	v_and_b32_e32 v5, 7, v0
	v_readlane_b32 s70, v254, 16
	v_readlane_b32 s71, v254, 17
	v_mov_b32_e32 v7, 0
	s_add_u32 s10, s50, 0x1c00000
	v_lshlrev_b32_e32 v6, 4, v5
	s_mov_b64 s[22:23], s[70:71]
	s_addc_u32 s11, s51, 0
	v_lshl_add_u64 v[16:17], s[22:23], 0, v[6:7]
	s_mov_b64 s[8:9], 0x1000
	v_lshrrev_b32_e32 v24, 3, v212
	s_add_u32 s2, s50, 0x1400000
	v_lshl_add_u64 v[16:17], v[16:17], 0, s[8:9]
	v_lshl_add_u64 v[18:19], s[50:51], 0, v[6:7]
	s_mov_b64 s[8:9], 0x800000
	v_lshlrev_b32_e32 v4, 2, v5
	v_lshlrev_b32_e32 v2, 3, v5
	v_mul_u32_u24_e32 v5, 0x420, v5
	v_lshlrev_b32_e32 v12, 2, v24
	s_addc_u32 s3, s51, 0
	v_lshl_add_u64 v[18:19], v[18:19], 0, s[8:9]
	s_mul_i32 s9, s81, 24
	v_lshl_add_u64 v[8:9], s[40:41], 0, v[6:7]
	v_add_u32_e32 v26, s28, v6
	v_mul_u32_u24_e32 v27, 0x84, v24
	v_lshl_add_u64 v[10:11], s[10:11], 0, v[6:7]
	v_add3_u32 v5, s28, v5, v12
	v_lshl_add_u64 v[12:13], s[44:45], 0, v[6:7]
	v_lshl_add_u64 v[14:15], s[2:3], 0, v[6:7]
	v_lshlrev_b32_e32 v6, 6, v212
	s_add_i32 s12, s53, s9
	s_mul_i32 s7, s20, 3
	v_lshl_add_u64 v[20:21], s[22:23], 0, v[6:7]
	v_lshlrev_b32_e32 v6, 5, v212
	s_mul_i32 s8, s81, 3
	s_add_i32 s9, s12, 0xf380
	s_lshl_b32 s14, s12, 5
	s_addk_i32 s12, 0x180
	v_add_u32_e32 v26, v26, v27
	v_or_b32_e32 v25, 8, v24
	v_or_b32_e32 v3, 16, v24
	v_or_b32_e32 v1, 24, v24
	v_lshl_add_u64 v[22:23], s[4:5], 0, v[6:7]
	s_addk_i32 s7, 0x1c2
	s_add_i32 s8, s8, 63
	s_movk_i32 s18, 0x4000
	s_add_i32 s19, s14, 0x4000
	s_lshl_b32 s14, s12, 12
	s_lshl_b32 s12, s12, 14
	v_add_u32_e32 v27, 0x420, v26
	v_add_u32_e32 v28, 0x428, v26
	v_add_u32_e32 v29, 0x840, v26
	v_add_u32_e32 v30, 0x848, v26
	v_add_u32_e32 v31, 0xc60, v26
	v_add_u32_e32 v32, 0xc68, v26
	v_add_u32_e32 v33, 0x1080, v26
	v_add_u32_e32 v34, 0x1088, v26
	v_add_u32_e32 v35, 0x14a0, v26
	v_add_u32_e32 v36, 0x14a8, v26
	v_add_u32_e32 v37, 0x18c0, v26
	v_add_u32_e32 v38, 0x18c8, v26
	v_add_u32_e32 v39, 0x1ce0, v26
	v_add_u32_e32 v40, 0x1ce8, v26
	s_mov_b32 s29, 0x20000
	s_mov_b32 s30, 0x40000
	s_mov_b32 s31, 0x60000
	s_mov_b32 s33, 0x80000
	s_mov_b32 s34, 0xa0000
	s_mov_b32 s35, 0xc0000
	s_mov_b32 s36, 0xe0000
	s_mov_b64 s[22:23], 0x4000
	s_mov_b64 s[24:25], 0x8000
	s_mov_b32 s37, 0x8000
	s_mov_b64 s[26:27], 0xc000
	s_mov_b32 s54, 0xc000
	s_movk_i32 s55, 0x1000
	v_readlane_b32 s57, v254, 3
	v_readlane_b32 s58, v254, 4
	v_readlane_b32 s59, v254, 5
	v_readlane_b32 s60, v254, 6
	v_readlane_b32 s61, v254, 7
	v_readlane_b32 s62, v254, 8
	v_readlane_b32 s63, v254, 9
	v_readlane_b32 s64, v254, 10
	v_readlane_b32 s65, v254, 11
	v_readlane_b32 s66, v254, 12
	v_readlane_b32 s67, v254, 13
	v_readlane_b32 s68, v254, 14
	v_readlane_b32 s69, v254, 15
	s_cmp_eq_u32 s99, 1
	s_cbranch_scc1 .LBB0_187
	s_cmpk_gt_i32 s81, 0x85
	s_cbranch_scc1 .LBB0_203
	s_branch .LBB0_187

; #define LAS __attribute__((address_space(3)))
; __device__ __forceinline__ f32x4 ld_nt(const float* p) { return __builtin_nontemporal_load((const f32x4*)p); }
; __device__ __forceinline__ void transpose_item(const float* W, int K, int pitch, int ncols, f16* WT, LAS float* scr, int item, int lane) {
;     const int nblk = ncols / 32, kb = item / nblk, nb = item % nblk, k0 = 64 * kb, n0 = 32 * nb;
;     const int kr = lane >> 3, nq = (lane & 7) * 4;
;     f32x4 v[8];
; #pragma unroll
;     for (int i = 0; i < 8; ++i) v[i] = ld_nt(W + (size_t)(k0 + kr + 8 * i) * pitch + n0 + nq);
;     __builtin_amdgcn_sched_barrier(0);
; #pragma unroll
;     for (int i = 0; i < 8; ++i) { LAS float* sp = scr + (kr + 8 * i) * 33 + nq; sp[0] = v[i][0]; sp[1] = v[i][1]; sp[2] = v[i][2]; sp[3] = v[i][3]; }
;     asm volatile("s_waitcnt lgkmcnt(0)" ::: "memory");
;     const int c = lane & 7;
; #pragma unroll
;     for (int j = 0; j < 4; ++j) { const int n = (lane >> 3) + 8 * j; const LAS float* sp = scr + (8 * c) * 33 + n;
;         u32x4 o; o.x = pk_f16(sp[0 * 33], sp[1 * 33]); o.y = pk_f16(sp[2 * 33], sp[3 * 33]); o.z = pk_f16(sp[4 * 33], sp[5 * 33]); o.w = pk_f16(sp[6 * 33], sp[7 * 33]);
;         *(u32x4*)(WT + (size_t)(n0 + n) * K + k0 + 8 * c) = o; }
;     asm volatile("s_waitcnt lgkmcnt(0)" ::: "memory");
; __global__ void __launch_bounds__(NTHREADS, 2) mk_fwd(Args a) {
;     ...
;                    if (b2 < 16) transpose_dispatch((832 + b2) * 8 + wave, a.in[7], a.in[20], a.in[18], a.in[8], a.ws, scr, lane); } );
.LBB0_203:
	s_cmp_eq_u32 s99, 1
	s_cbranch_scc1 .Lp3_tr_ret
	s_cmpk_lt_i32 s81, 0x90
	s_cbranch_scc0 .LBB0_212
	s_add_i32 s7, s6, 0x1600
	s_cmpk_gt_i32 s7, 0x7f
	s_mov_b64 s[12:13], -1
	s_cbranch_scc0 .LBB0_210
	s_lshl_b32 s8, s7, 5
	s_and_b32 s8, s8, 0x7e0
	s_cmpk_gt_u32 s7, 0x167f
	s_mov_b32 s13, 0
	s_mov_b64 s[14:15], -1
	v_or_b32_e32 v9, s8, v24
	v_or_b32_e32 v8, s8, v25
	v_or_b32_e32 v7, s8, v3
	v_or_b32_e32 v6, s8, v1
	s_cbranch_scc0 .LBB0_207
	s_and_b32 s9, s7, 0x7fffffc0
	s_add_i32 s12, s9, 0xffffe980
	s_lshl_b32 s9, s8, 2
	s_add_u32 s14, s40, s9
	v_or_b32_e32 v22, s12, v24
	s_addc_u32 s15, s41, 0
	v_lshlrev_b32_e32 v48, 2, v4
	v_mov_b32_e32 v49, 0
	v_lshl_add_u64 v[40:41], s[14:15], 0, v[48:49]
	v_or_b32_e32 v48, 8, v22
	v_lshlrev_b64 v[12:13], 13, v[48:49]
	v_or_b32_e32 v48, 16, v22
	v_lshlrev_b64 v[18:19], 13, v[48:49]
	v_or_b32_e32 v48, 24, v22
	v_lshlrev_b64 v[20:21], 13, v[48:49]
	v_or_b32_e32 v48, 32, v22
	v_lshlrev_b64 v[32:33], 13, v[48:49]
	v_or_b32_e32 v48, 40, v22
	v_mov_b32_e32 v23, v49
	v_lshlrev_b64 v[34:35], 13, v[48:49]
	v_or_b32_e32 v48, 48, v22
	v_lshlrev_b64 v[10:11], 13, v[22:23]
	v_lshlrev_b64 v[42:43], 13, v[48:49]
	v_or_b32_e32 v48, 56, v22
	v_lshl_add_u64 v[10:11], v[40:41], 0, v[10:11]
	v_lshl_add_u64 v[14:15], v[40:41], 0, v[12:13]
	v_lshl_add_u64 v[18:19], v[40:41], 0, v[18:19]
	v_lshl_add_u64 v[28:29], v[40:41], 0, v[20:21]
	v_lshl_add_u64 v[32:33], v[40:41], 0, v[32:33]
	v_lshl_add_u64 v[36:37], v[40:41], 0, v[34:35]
	v_lshl_add_u64 v[42:43], v[40:41], 0, v[42:43]
	v_lshlrev_b64 v[22:23], 13, v[48:49]
	global_load_dwordx4 v[10:13], v[10:11], off nt
	s_nop 0
	global_load_dwordx4 v[14:17], v[14:15], off nt
	s_nop 0
	global_load_dwordx4 v[18:21], v[18:19], off nt
	s_nop 0
	global_load_dwordx4 v[28:31], v[28:29], off nt
	s_nop 0
	global_load_dwordx4 v[32:35], v[32:33], off nt
	s_nop 0
	global_load_dwordx4 v[36:39], v[36:37], off nt
	v_lshl_add_u64 v[22:23], v[40:41], 0, v[22:23]
	global_load_dwordx4 v[40:43], v[42:43], off nt
	s_nop 0
	global_load_dwordx4 v[44:47], v[22:23], off nt
	s_waitcnt vmcnt(0)
	ds_write2_b32 v26, v10, v11 offset1:1
	ds_write2_b32 v26, v12, v13 offset0:2 offset1:3
	v_add_u32_e32 v10, 0x420, v26
	ds_write2_b32 v10, v14, v15 offset1:1
	v_add_u32_e32 v10, 0x428, v26
	ds_write2_b32 v10, v16, v17 offset1:1
	v_add_u32_e32 v10, 0x840, v26
	ds_write2_b32 v10, v18, v19 offset1:1
	v_add_u32_e32 v10, 0x848, v26
	ds_write2_b32 v10, v20, v21 offset1:1
	v_add_u32_e32 v10, 0xc60, v26
	ds_write2_b32 v10, v28, v29 offset1:1
	v_add_u32_e32 v10, 0xc68, v26
	ds_write2_b32 v10, v30, v31 offset1:1
	v_add_u32_e32 v10, 0x1080, v26
	ds_write2_b32 v10, v32, v33 offset1:1
	v_add_u32_e32 v10, 0x1088, v26
	ds_write2_b32 v10, v34, v35 offset1:1
	v_add_u32_e32 v10, 0x14a0, v26
	ds_write2_b32 v10, v36, v37 offset1:1
	v_add_u32_e32 v10, 0x14a8, v26
	ds_write2_b32 v10, v38, v39 offset1:1
	v_add_u32_e32 v10, 0x18c0, v26
	ds_write2_b32 v10, v40, v41 offset1:1
	v_add_u32_e32 v10, 0x18c8, v26
	ds_write2_b32 v10, v42, v43 offset1:1
	v_add_u32_e32 v10, 0x1ce0, v26
	ds_write2_b32 v10, v44, v45 offset1:1
	v_add_u32_e32 v10, 0x1ce8, v26
	ds_write2_b32 v10, v46, v47 offset1:1
	s_waitcnt lgkmcnt(0)
	ds_read2_b32 v[14:15], v5 offset0:33 offset1:41
	ds_read2_b32 v[16:17], v5 offset1:8
	ds_read2_b32 v[18:19], v5 offset0:66 offset1:74
	ds_read2_b32 v[20:21], v5 offset0:99 offset1:107
	ds_read2_b32 v[22:23], v5 offset0:132 offset1:140
	ds_read2_b32 v[28:29], v5 offset0:165 offset1:173
	ds_read2_b32 v[30:31], v5 offset0:198 offset1:206
	ds_read2_b32 v[32:33], v5 offset0:231 offset1:239
	s_lshl_b64 s[12:13], s[12:13], 1
	s_add_u32 s10, s10, s12
	s_addc_u32 s11, s11, s13
	v_lshlrev_b32_e32 v48, 1, v2
	v_lshl_add_u64 v[34:35], s[10:11], 0, v[48:49]
	v_lshlrev_b32_e32 v48, 11, v9
	s_waitcnt lgkmcnt(6)
	v_cvt_pk_bf16_f32 v10, v16, v14
	s_waitcnt lgkmcnt(4)
	v_cvt_pk_bf16_f32 v11, v18, v20
	s_waitcnt lgkmcnt(2)
	v_cvt_pk_bf16_f32 v12, v22, v28
	s_waitcnt lgkmcnt(0)
	v_cvt_pk_bf16_f32 v13, v30, v32
	v_lshl_add_u64 v[36:37], v[34:35], 0, v[48:49]
	global_store_dwordx4 v[36:37], v[10:13], off
	v_lshlrev_b32_e32 v48, 11, v8
	s_mov_b64 s[14:15], 0
	v_cvt_pk_bf16_f32 v10, v17, v15
	v_cvt_pk_bf16_f32 v11, v19, v21
	v_cvt_pk_bf16_f32 v12, v23, v29
	v_cvt_pk_bf16_f32 v13, v31, v33
	ds_read2_b32 v[16:17], v5 offset0:49 offset1:57
	ds_read2_b32 v[18:19], v5 offset0:16 offset1:24
	ds_read2_b32 v[20:21], v5 offset0:82 offset1:90
	ds_read2_b32 v[22:23], v5 offset0:115 offset1:123
	ds_read2_b32 v[28:29], v5 offset0:148 offset1:156
	ds_read2_b32 v[30:31], v5 offset0:181 offset1:189
	ds_read2_b32 v[32:33], v5 offset0:214 offset1:222
	ds_read2_b32 v[36:37], v5 offset0:247 offset1:255
	v_lshl_add_u64 v[14:15], v[34:35], 0, v[48:49]
	v_lshlrev_b32_e32 v48, 11, v7
	global_store_dwordx4 v[14:15], v[10:13], off
	v_lshl_add_u64 v[14:15], v[34:35], 0, v[48:49]
	v_lshlrev_b32_e32 v48, 11, v6
	s_waitcnt lgkmcnt(6)
	v_cvt_pk_bf16_f32 v10, v18, v16
	s_waitcnt lgkmcnt(4)
	v_cvt_pk_bf16_f32 v11, v20, v22
	s_waitcnt lgkmcnt(2)
	v_cvt_pk_bf16_f32 v12, v28, v30
	s_waitcnt lgkmcnt(0)
	v_cvt_pk_bf16_f32 v13, v32, v36
	global_store_dwordx4 v[14:15], v[10:13], off
	v_lshl_add_u64 v[14:15], v[34:35], 0, v[48:49]
	s_nop 0
	v_cvt_pk_bf16_f32 v10, v19, v17
	v_cvt_pk_bf16_f32 v11, v21, v23
	v_cvt_pk_bf16_f32 v12, v29, v31
	v_cvt_pk_bf16_f32 v13, v33, v37
	global_store_dwordx4 v[14:15], v[10:13], off
	s_waitcnt lgkmcnt(0)

; #define SUB(i, ...) do { if (PROBE_PH == phk && PROBE_SUB == (i)) { __syncthreads(); tp0 = __builtin_amdgcn_s_memrealtime(); } __VA_ARGS__ if (PROBE_PH == phk && PROBE_SUB == (i)) { asm volatile("s_waitcnt vmcnt(0)" ::: "memory"); __syncthreads(); tp1 = __builtin_amdgcn_s_memrealtime(); } } while (0)
; __global__ void __launch_bounds__(NTHREADS, 2) mk_fwd(Args a) {
;     ...
;         SUB(2, if (vcu < 128) transpose_dispatch((320 + vcu) * 8 + wave, a.in[7], a.in[20], a.in[18], a.in[8], a.ws, scr, lane);
;                else { const int b2 = vcu - 128;
;                    for (int it = 448 + 3 * b2; it < 448 + 3 * b2 + 3; ++it) transpose_dispatch(it * 8 + wave, a.in[7], a.in[20], a.in[18], a.in[8], a.ws, scr, lane);
;                    if (b2 < 16) transpose_dispatch((832 + b2) * 8 + wave, a.in[7], a.in[20], a.in[18], a.in[8], a.ws, scr, lane); } );
;     ...
;     PHASE(3,
;         const int ridx = vcu >> 1;
;         const int sg = ridx >> 1, sb = ridx & 1;
;         unsigned* f1 = ctl + 8192 + ridx; unsigned* f2 = f1 + 128; unsigned* f3 = f1 + 256;
;         pg8::OneUnit SZ; SZ.u.g = 0; SZ.u.pm = 16 * ((bx & 7) >> 1) + (bx >> 4); SZ.u.pn = 12 + 2 * (bx & 1) + ((bx >> 3) & 1); SZ.have = true;
;         EpiInProj EZ{(f16*)(a.ws + WS_UPOOL), (f16*)(a.ws + WS_X), (f16*)(a.ws + WS_ZS)};
;         if (!(vcu & 1)) {
.LBB0_490:
	s_cmp_lt_i32 s78, 4
	s_cselect_b64 s[0:1], -1, 0
	s_and_b64 s[90:91], s[0:1], s[2:3]
	s_andn2_b64 vcc, exec, s[90:91]
	s_cbranch_vccnz .LBB0_997
	s_bitcmp1_b32 s81, 0
	s_cbranch_scc0 .Lp3_tr_skip
	s_lshr_b32 s100, s81, 1
	s_cmp_lt_u32 s100, 6
	s_cbranch_scc1 .Lp3_tr_skip
	s_mov_b32 s98, s81
	s_add_i32 s81, s100, 0x80
	s_mov_b32 s20, s100
	s_mov_b32 s99, 1
	s_mov_b32 s13, 0
	s_mul_i32 s28, s53, 0x2100
	v_and_b32_e32 v212, 63, v0
	v_readlane_b32 s100, v254, 0
	v_readlane_b32 s101, v254, 1
	s_nop 3
	s_sub_u32 s100, s100, 0xc8
	s_subb_u32 s101, s101, 0
	s_add_u32 s0, s50, 0x2000000
	s_addc_u32 s1, s51, 0
	s_add_u32 s4, s50, 0x13600000
	s_addc_u32 s5, s51, 0
	s_load_dwordx2 s[40:41], s[100:101], 0x90
	s_load_dwordx2 s[44:45], s[100:101], 0xa0
	s_waitcnt lgkmcnt(0)
	s_branch .Lp1_tr_setup
.Lp3_tr_ret:
	s_mov_b32 s81, s98
	s_mov_b32 s99, 0
	s_waitcnt lgkmcnt(0)
	s_barrier
.Lp3_tr_skip:
	s_ashr_i32 s34, s81, 1
	s_ashr_i32 s35, s34, 31
	s_ashr_i32 s24, s81, 2
	s_and_b32 s84, s34, 1
	s_lshl_b64 s[0:1], s[34:35], 2
	s_add_u32 s0, s50, s0
	s_addc_u32 s1, s51, s1
	s_add_u32 s26, s0, 0x8000
	s_addc_u32 s27, s1, 0
	s_lshl_b32 s0, s16, 3
	s_and_b32 s0, s0, 48
	s_ashr_i32 s1, s16, 4
	s_add_i32 s30, s0, s1
	s_lshl_b32 s0, s16, 1
	s_and_b32 s76, s0, 2
	s_bfe_u32 s77, s16, 0x10003
	s_or_b32 s0, s77, s76
	s_or_b32 s29, s0, 12
	s_add_u32 s22, s50, 0xc300000
	s_addc_u32 s23, s51, 0
	s_add_u32 s92, s50, 0xf600000
	s_addc_u32 s93, s51, 0
	s_bitcmp1_b32 s81, 0
	s_cselect_b64 s[0:1], -1, 0
	s_and_b64 vcc, exec, s[0:1]
	s_mul_hi_i32 s85, s24, 0xc6000
	s_mul_i32 s86, s24, 0xc6000
	s_cbranch_vccz .LBB0_529
	v_readfirstlane_b32 s0, v0
	s_lshr_b32 s12, s0, 6
	s_ashr_i32 s31, s30, 31
	s_lshr_b32 s13, s0, 8
	s_lshl_b32 s70, s12, 10
	s_lshl_b64 s[20:21], s[30:31], 20
	s_add_u32 s1, s50, s20
	v_lshrrev_b32_e32 v1, 5, v0
	v_bfe_u32 v2, v0, 2, 2
	s_addc_u32 s3, s51, s21
	v_and_or_b32 v1, v1, 4, v2
	v_lshrrev_b32_e32 v2, 3, v0
	v_lshrrev_b32_e32 v4, 1, v0
	s_add_u32 s2, s1, 0x6100000
	v_and_b32_e32 v3, 32, v2
	v_and_b32_e32 v215, 24, v4
	s_addc_u32 s3, s3, 0
	s_lshl_b32 s1, s29, 20
	v_or3_b32 v216, v1, v3, v215
	v_lshlrev_b32_e32 v213, 4, v0
	v_and_b32_e32 v1, 32, v0
	s_add_u32 s1, s50, s1
	v_bitop3_b32 v6, v213, v1, 48 bitop3:0x6c
	v_and_b32_e32 v7, 64, v0
	s_addc_u32 s5, s51, 0
	v_or_b32_e32 v214, v6, v7
	s_add_u32 s4, s1, 0x400000
	v_lshl_or_b32 v130, v216, 12, v214
	v_bfe_u32 v8, v0, 2, 4
	s_addc_u32 s5, s5, 0
	v_mov_b32_e32 v131, 0
	s_add_i32 s1, s70, 0
	v_and_or_b32 v219, v2, 48, v8
	v_lshl_add_u64 v[2:3], s[4:5], 0, v[130:131]
	s_add_i32 m0, s1, 0x10000
	s_mov_b64 s[6:7], 0x40000
	global_load_lds_dwordx4 v130, s[4:5]
	v_lshl_add_u64 v[4:5], v[2:3], 0, s[6:7]
	s_add_i32 m0, s1, 0x12000
	s_mov_b64 s[8:9], 0x80000
	global_load_lds_dwordx4 v[4:5], off
	v_lshl_add_u64 v[4:5], v[2:3], 0, s[8:9]
	s_add_i32 m0, s1, 0x14000
	s_mov_b64 s[10:11], 0xc0000
	v_lshl_or_b32 v132, v219, 12, v214
	global_load_lds_dwordx4 v[4:5], off
	v_lshl_add_u64 v[4:5], v[2:3], 0, s[10:11]
	s_add_i32 m0, s1, 0x16000
	v_mov_b32_e32 v133, v131
	global_load_lds_dwordx4 v[4:5], off
	v_lshl_add_u64 v[4:5], s[2:3], 0, v[132:133]
	s_mov_b32 m0, s1
	s_add_i32 s31, s1, 0x2000
	global_load_lds_dwordx4 v132, s[2:3]
	v_lshl_add_u64 v[10:11], v[4:5], 0, s[6:7]
	s_mov_b32 m0, s31
	s_add_i32 s33, s1, 0x4000
	global_load_lds_dwordx4 v[10:11], off
	v_lshl_add_u64 v[10:11], v[4:5], 0, s[8:9]
	s_mov_b32 m0, s33
	s_add_i32 s35, s1, 0x6000
	global_load_lds_dwordx4 v[10:11], off
	v_lshl_add_u64 v[10:11], v[4:5], 0, s[10:11]
	s_mov_b32 m0, s35
	s_mov_b32 s28, s81
	global_load_lds_dwordx4 v[10:11], off
	s_cmp_lg_u32 s13, 1
	s_cbranch_scc1 .LBB0_494
	s_barrier
